# rowop<1> ctx rows: gpre/sc/sh loads of column chunks 1-3 issued together with chunk 0 (counted vmcnt)
# baseline (speedup 1.0000x reference)
.LBB0_34:
	v_cmp_gt_i32_e32 vcc, 0, v40
	v_min_i32_e32 v0, 0x4000, v26
	v_mov_b32_e32 v2, s23
	v_mov_b32_e32 v3, s89
	v_ashrrev_i32_e32 v31, 13, v0
	v_cndmask_b32_e32 v1, 0, v27, vcc
	v_cndmask_b32_e32 v0, v40, v26, vcc
	v_cndmask_b32_e32 v3, v2, v3, vcc
	v_mov_b32_e32 v2, s22
	v_mov_b32_e32 v4, s88
	v_cndmask_b32_e32 v2, v2, v4, vcc
	v_lshlrev_b64 v[0:1], 12, v[0:1]
	v_lshl_add_u64 v[0:1], v[2:3], 0, v[0:1]
	v_lshl_add_u64 v[36:37], v[0:1], 0, v[192:193]
	global_load_dwordx4 v[12:15], v[36:37], off nt
	global_load_dwordx4 v[8:11], v[36:37], off offset:1024 nt
	global_load_dwordx4 v[4:7], v[36:37], off offset:2048 nt
	global_load_dwordx4 v[0:3], v[36:37], off offset:3072 nt
	global_load_dwordx2 v[56:57], v[28:29], off nt
	global_load_dwordx2 v[64:65], v[28:29], off offset:512 nt
	global_load_dwordx2 v[72:73], v[28:29], off offset:1024 nt
	global_load_dwordx2 v[80:81], v[28:29], off offset:1536 nt
	v_mul_hi_i32_i24_e32 v39, 0x6000, v31
	v_mul_i32_i24_e32 v38, 0x6000, v31
	v_lshl_add_u64 v[38:39], s[90:91], 0, v[38:39]
	s_waitcnt vmcnt(11)
	v_lshl_add_u64 v[52:53], v[38:39], 0, v[192:193]
	v_lshl_add_u64 v[76:77], v[52:53], 0, s[34:35]
	v_add_co_u32_e32 v52, vcc, s24, v52
	global_load_dwordx4 v[48:51], v[16:17], off
	s_nop 0
	v_addc_co_u32_e32 v53, vcc, 0, v53, vcc
	global_load_dwordx4 v[52:55], v[52:53], off
	s_mov_b32 s4, 0xf823c000
	v_add_u32_e32 v40, s20, v40
	v_lshl_add_u64 v[26:27], v[26:27], 0, s[20:21]
	s_waitcnt vmcnt(5)
	v_and_b32_e32 v39, 0xffff0000, v56
	s_waitcnt vmcnt(4)
	v_and_b32_e32 v85, 0xffff0000, v64
	v_lshlrev_b32_e32 v38, 16, v56
	v_lshlrev_b32_e32 v84, 16, v64
	v_mov_b32_e32 v66, v39
	v_mov_b32_e32 v67, v85
	v_lshlrev_b32_e32 v82, 16, v57
	v_and_b32_e32 v87, 0xffff0000, v65
	v_lshlrev_b32_e32 v86, 16, v65
	v_mov_b32_e32 v64, v38
	v_mov_b32_e32 v65, v84
	v_pk_mul_f32 v[66:67], v[66:67], v[66:67]
	v_and_b32_e32 v83, 0xffff0000, v57
	global_load_dwordx4 v[56:59], v[16:17], off offset:1024
	global_load_dwordx4 v[60:63], v[76:77], off offset:1024
	v_pk_fma_f32 v[64:65], v[64:65], v[64:65], v[66:67]
	v_mov_b32_e32 v66, v82
	v_mov_b32_e32 v67, v86
	v_mov_b32_e32 v68, v83
	v_mov_b32_e32 v69, v87
	v_pk_fma_f32 v[64:65], v[66:67], v[66:67], v[64:65]
	s_waitcnt vmcnt(5)
	v_and_b32_e32 v91, 0xffff0000, v72
	v_pk_fma_f32 v[88:89], v[68:69], v[68:69], v[64:65]
	global_load_dwordx4 v[64:67], v[16:17], off offset:2048
	global_load_dwordx4 v[68:71], v[76:77], off offset:2048
	v_lshlrev_b32_e32 v90, 16, v72
	v_and_b32_e32 v93, 0xffff0000, v73
	v_lshlrev_b32_e32 v92, 16, v73
	global_load_dwordx4 v[72:75], v[16:17], off offset:3072
	s_nop 0
	global_load_dwordx4 v[76:79], v[76:77], off offset:3072
	s_waitcnt vmcnt(8)
	v_and_b32_e32 v95, 0xffff0000, v80
	v_lshlrev_b32_e32 v94, 16, v80
	v_mov_b32_e32 v98, v91
	v_mov_b32_e32 v99, v95
	v_and_b32_e32 v97, 0xffff0000, v81
	v_lshlrev_b32_e32 v96, 16, v81
	v_mov_b32_e32 v80, v90
	v_mov_b32_e32 v81, v94
	v_pk_mul_f32 v[98:99], v[98:99], v[98:99]
	v_mov_b32_e32 v100, v93
	v_pk_fma_f32 v[80:81], v[80:81], v[80:81], v[98:99]
	v_mov_b32_e32 v98, v92
	v_mov_b32_e32 v99, v96
	v_mov_b32_e32 v101, v97
	v_pk_fma_f32 v[80:81], v[98:99], v[98:99], v[80:81]
	v_add_f32_e32 v33, v88, v89
	v_pk_fma_f32 v[80:81], v[100:101], v[100:101], v[80:81]
	s_nop 0
	v_add_f32_e32 v33, v33, v80
	v_add_f32_e32 v33, v33, v81
	ds_bpermute_b32 v35, v41, v33
	s_waitcnt lgkmcnt(0)
	v_add_f32_e32 v33, v33, v35
	ds_bpermute_b32 v35, v42, v33
	s_waitcnt lgkmcnt(0)
	v_add_f32_e32 v33, v33, v35
	ds_bpermute_b32 v35, v43, v33
	s_waitcnt lgkmcnt(0)
	v_add_f32_e32 v33, v33, v35
	ds_bpermute_b32 v35, v44, v33
	s_waitcnt lgkmcnt(0)
	v_add_f32_e32 v33, v33, v35
	ds_bpermute_b32 v35, v45, v33
	s_waitcnt lgkmcnt(0)
	v_add_f32_e32 v33, v33, v35
	ds_bpermute_b32 v35, v46, v33
	s_waitcnt lgkmcnt(0)
	v_add_f32_e32 v33, v33, v35
	v_fmamk_f32 v33, v33, 0x3a800000, v219
	v_cmp_gt_f32_e32 vcc, s25, v33
	v_mul_f32_e32 v35, 0x4b800000, v33
	s_nop 0
	v_cndmask_b32_e32 v33, v33, v35, vcc
	v_rsq_f32_e32 v33, v33
	s_nop 0
	v_mul_f32_e32 v35, 0x45800000, v33
	v_cndmask_b32_e32 v80, v33, v35, vcc
	v_pk_mul_f32 v[38:39], v[80:81], v[38:39] op_sel_hi:[0,1]
	s_waitcnt vmcnt(7)
	v_pk_mul_f32 v[38:39], v[48:49], v[38:39]
	v_pk_mul_f32 v[48:49], v[80:81], v[82:83] op_sel_hi:[0,1]
	v_pk_mul_f32 v[50:51], v[50:51], v[48:49]
	s_waitcnt vmcnt(6)
	v_pk_fma_f32 v[48:49], v[52:53], v[38:39], v[12:13]
	v_pk_mul_f32 v[12:13], v[80:81], v[84:85] op_sel_hi:[0,1]
	v_pk_fma_f32 v[50:51], v[54:55], v[50:51], v[14:15]
	s_waitcnt vmcnt(5)
	v_pk_mul_f32 v[12:13], v[56:57], v[12:13]
	v_pk_mul_f32 v[14:15], v[80:81], v[86:87] op_sel_hi:[0,1]
	v_pk_mul_f32 v[14:15], v[58:59], v[14:15]
	s_waitcnt vmcnt(4)
	v_pk_fma_f32 v[8:9], v[60:61], v[12:13], v[8:9]
	v_pk_mul_f32 v[12:13], v[80:81], v[90:91] op_sel_hi:[0,1]
	v_pk_fma_f32 v[10:11], v[62:63], v[14:15], v[10:11]
	s_waitcnt vmcnt(3)
	v_pk_mul_f32 v[12:13], v[12:13], v[64:65]
	v_pk_mul_f32 v[14:15], v[80:81], v[92:93] op_sel_hi:[0,1]
	v_pk_mul_f32 v[14:15], v[14:15], v[66:67]
	s_waitcnt vmcnt(2)
	v_pk_fma_f32 v[4:5], v[12:13], v[68:69], v[4:5]
	v_pk_mul_f32 v[12:13], v[80:81], v[94:95] op_sel_hi:[0,1]
	v_pk_fma_f32 v[6:7], v[14:15], v[70:71], v[6:7]
	s_waitcnt vmcnt(1)
	v_pk_mul_f32 v[12:13], v[12:13], v[72:73]
	v_pk_mul_f32 v[14:15], v[80:81], v[96:97] op_sel_hi:[0,1]
	v_pk_mul_f32 v[14:15], v[14:15], v[74:75]
	s_waitcnt vmcnt(0)
	v_pk_fma_f32 v[0:1], v[12:13], v[76:77], v[0:1]
	v_add_u32_e32 v12, 3, v31
	v_pk_fma_f32 v[2:3], v[14:15], v[78:79], v[2:3]
	global_store_dwordx4 v[36:37], v[48:51], off nt
	global_store_dwordx4 v[36:37], v[8:11], off offset:1024 nt
	global_store_dwordx4 v[36:37], v[4:7], off offset:2048 nt
	global_store_dwordx4 v[36:37], v[0:3], off offset:3072 nt
	v_mul_hi_i32_i24_e32 v13, 0x6000, v12
	v_mul_i32_i24_e32 v12, 0x6000, v12
	v_mov_b32_e32 v36, v49
	v_mov_b32_e32 v37, v9
	v_lshl_add_u64 v[14:15], s[96:97], 0, v[12:13]
	v_mov_b32_e32 v12, v48
	v_mov_b32_e32 v13, v8
	v_pk_mul_f32 v[36:37], v[36:37], v[36:37]
	v_mov_b32_e32 v38, v5
	v_pk_fma_f32 v[12:13], v[12:13], v[12:13], v[36:37]
	v_mov_b32_e32 v36, v50
	v_mov_b32_e32 v37, v10
	v_pk_fma_f32 v[12:13], v[36:37], v[36:37], v[12:13]
	v_mov_b32_e32 v36, v51
	v_mov_b32_e32 v37, v11
	v_mov_b32_e32 v39, v1
	v_pk_fma_f32 v[12:13], v[36:37], v[36:37], v[12:13]
	v_mov_b32_e32 v36, v4
	v_mov_b32_e32 v37, v0
	v_pk_mul_f32 v[38:39], v[38:39], v[38:39]
	v_add_f32_e32 v12, v12, v13
	v_pk_fma_f32 v[36:37], v[36:37], v[36:37], v[38:39]
	v_mov_b32_e32 v38, v6
	v_mov_b32_e32 v39, v2
	v_pk_fma_f32 v[36:37], v[38:39], v[38:39], v[36:37]
	v_mov_b32_e32 v38, v7
	v_mov_b32_e32 v39, v3
	v_pk_fma_f32 v[36:37], v[38:39], v[38:39], v[36:37]
	s_nop 0
	v_add_f32_e32 v12, v12, v36
	v_add_f32_e32 v12, v12, v37
	v_lshl_add_u64 v[36:37], v[14:15], 0, s[28:29]
	v_lshl_add_u64 v[38:39], v[36:37], 0, v[192:193]
	v_lshl_add_u64 v[14:15], v[14:15], 0, v[192:193]
	global_load_dwordx4 v[52:55], v[18:19], off
	global_load_dwordx4 v[56:59], v[38:39], off
	global_load_dwordx4 v[60:63], v[14:15], off
	global_load_dwordx4 v[106:109], v[20:21], off
	v_mov_b32_e32 v110, v30
	v_mov_b32_e32 v111, v193
	v_lshl_add_u64 v[110:111], v[36:37], 0, v[110:111]
	global_load_dwordx4 v[116:119], v[110:111], off
	global_load_dwordx4 v[120:123], v[14:15], off offset:1024
	global_load_dwordx4 v[124:127], v[22:23], off
	v_mov_b32_e32 v110, v32
	v_mov_b32_e32 v111, v193
	v_lshl_add_u64 v[110:111], v[36:37], 0, v[110:111]
	global_load_dwordx4 v[136:139], v[110:111], off
	global_load_dwordx4 v[140:143], v[14:15], off offset:2048
	global_load_dwordx4 v[144:147], v[24:25], off
	v_mov_b32_e32 v110, v34
	v_mov_b32_e32 v111, v193
	v_lshl_add_u64 v[110:111], v[36:37], 0, v[110:111]
	global_load_dwordx4 v[148:151], v[110:111], off
	global_load_dwordx4 v[152:155], v[14:15], off offset:3072
	ds_bpermute_b32 v13, v41, v12
	v_mov_b32_e32 v38, v48
	v_mov_b32_e32 v39, v50
	v_mov_b32_e32 v50, v49
	s_waitcnt lgkmcnt(0)
	v_add_f32_e32 v12, v12, v13
	ds_bpermute_b32 v13, v42, v12
	s_waitcnt lgkmcnt(0)
	v_add_f32_e32 v12, v12, v13
	ds_bpermute_b32 v13, v43, v12
	s_waitcnt lgkmcnt(0)
	v_add_f32_e32 v12, v12, v13
	ds_bpermute_b32 v13, v44, v12
	s_waitcnt lgkmcnt(0)
	v_add_f32_e32 v12, v12, v13
	ds_bpermute_b32 v13, v45, v12
	s_waitcnt lgkmcnt(0)
	v_add_f32_e32 v12, v12, v13
	ds_bpermute_b32 v13, v46, v12
	s_waitcnt lgkmcnt(0)
	v_add_f32_e32 v12, v12, v13
	v_fmamk_f32 v12, v12, 0x3a800000, v219
	v_cmp_gt_f32_e32 vcc, s25, v12
	v_mul_f32_e32 v13, 0x4b800000, v12
	s_waitcnt vmcnt(11)
	v_mov_b32_e32 v64, v52
	v_cndmask_b32_e32 v12, v12, v13, vcc
	v_rsq_f32_e32 v12, v12
	v_mov_b32_e32 v65, v54
	v_mov_b32_e32 v54, v53
	s_waitcnt vmcnt(9)
	v_mov_b32_e32 v67, v62
	v_mul_f32_e32 v13, 0x45800000, v12
	v_cndmask_b32_e32 v12, v12, v13, vcc
	v_pk_mul_f32 v[38:39], v[38:39], v[12:13] op_sel_hi:[1,0]
	v_pk_mul_f32 v[48:49], v[50:51], v[12:13] op_sel_hi:[1,0]
	v_pk_mul_f32 v[38:39], v[64:65], v[38:39]
	v_mov_b32_e32 v65, v58
	v_mov_b32_e32 v58, v57
	v_mov_b32_e32 v64, v56
	v_pk_mul_f32 v[48:49], v[54:55], v[48:49]
	v_pk_add_f32 v[50:51], v[58:59], 1.0 op_sel_hi:[1,0]
	v_mov_b32_e32 v62, v61
	v_pk_add_f32 v[64:65], v[64:65], 1.0 op_sel_hi:[1,0]
	v_mov_b32_e32 v66, v60
	v_pk_fma_f32 v[48:49], v[50:51], v[48:49], v[62:63]
	v_pk_fma_f32 v[38:39], v[64:65], v[38:39], v[66:67]
	v_and_b32_sdwa v33, v49, v218 dst_sel:DWORD dst_unused:UNUSED_PAD src0_sel:WORD_1 src1_sel:DWORD
	v_and_b32_sdwa v13, v39, v218 dst_sel:DWORD dst_unused:UNUSED_PAD src0_sel:WORD_1 src1_sel:DWORD
	v_cvt_pk_bf16_f32 v38, v38, v48
	v_add3_u32 v33, v49, v33, s80
	v_add3_u32 v13, v39, v13, s80
	v_and_b32_e32 v33, 0xffff0000, v33
	v_add_co_u32_e32 v48, vcc, s4, v28
	v_or_b32_sdwa v39, v33, v13 dst_sel:DWORD dst_unused:UNUSED_PAD src0_sel:DWORD src1_sel:WORD_1
	s_nop 0
	v_addc_co_u32_e32 v49, vcc, -1, v29, vcc
	global_store_dwordx2 v[48:49], v[38:39], off nt
	v_mov_b32_e32 v31, v193
	v_lshl_add_u64 v[38:39], v[36:37], 0, v[30:31]
	s_waitcnt vmcnt(7)
	v_mov_b32_e32 v48, v106
	v_mov_b32_e32 v49, v107
	v_mov_b32_e32 v50, v108
	v_mov_b32_e32 v51, v109
	v_mov_b32_e32 v52, v116
	v_mov_b32_e32 v53, v117
	v_mov_b32_e32 v54, v118
	v_mov_b32_e32 v55, v119
	v_mov_b32_e32 v56, v120
	v_mov_b32_e32 v57, v121
	v_mov_b32_e32 v58, v122
	v_mov_b32_e32 v59, v123
	v_mov_b32_e32 v38, v8
	v_mov_b32_e32 v39, v10
	v_pk_mul_f32 v[38:39], v[38:39], v[12:13] op_sel_hi:[1,0]
	v_mov_b32_e32 v10, v9
	v_pk_mul_f32 v[8:9], v[10:11], v[12:13] op_sel_hi:[1,0]
	s_mov_b32 s4, 0xf823d000
	v_mov_b32_e32 v33, v193
	v_mov_b32_e32 v35, v193
	v_mov_b32_e32 v60, v48
	v_mov_b32_e32 v61, v50
	v_pk_mul_f32 v[38:39], v[38:39], v[60:61]
	v_mov_b32_e32 v60, v52
	v_mov_b32_e32 v61, v54
	v_pk_add_f32 v[60:61], v[60:61], 1.0 op_sel_hi:[1,0]
	v_mov_b32_e32 v62, v56
	v_mov_b32_e32 v63, v58
	v_mov_b32_e32 v50, v49
	v_mov_b32_e32 v54, v53
	v_pk_fma_f32 v[38:39], v[38:39], v[60:61], v[62:63]
	v_pk_mul_f32 v[8:9], v[8:9], v[50:51]
	v_pk_add_f32 v[10:11], v[54:55], 1.0 op_sel_hi:[1,0]
	v_mov_b32_e32 v58, v57
	v_pk_fma_f32 v[8:9], v[8:9], v[10:11], v[58:59]
	v_and_b32_sdwa v11, v38, v218 dst_sel:DWORD dst_unused:UNUSED_PAD src0_sel:WORD_1 src1_sel:DWORD
	v_add3_u32 v13, v38, v11, s80
	v_and_b32_sdwa v31, v8, v218 dst_sel:DWORD dst_unused:UNUSED_PAD src0_sel:WORD_1 src1_sel:DWORD
	v_cvt_pk_bf16_f32 v11, v39, v9
	v_add3_u32 v8, v8, v31, s80
	v_and_b32_e32 v8, 0xffff0000, v8
	v_or_b32_sdwa v10, v8, v13 dst_sel:DWORD dst_unused:UNUSED_PAD src0_sel:DWORD src1_sel:WORD_1
	v_add_co_u32_e32 v8, vcc, s4, v28
	s_nop 1
	v_addc_co_u32_e32 v9, vcc, -1, v29, vcc
	global_store_dwordx2 v[8:9], v[10:11], off offset:-3584 nt
	v_lshl_add_u64 v[10:11], v[36:37], 0, v[32:33]
	s_waitcnt vmcnt(5)
	v_mov_b32_e32 v48, v124
	v_mov_b32_e32 v49, v125
	v_mov_b32_e32 v50, v126
	v_mov_b32_e32 v51, v127
	v_mov_b32_e32 v52, v136
	v_mov_b32_e32 v53, v137
	v_mov_b32_e32 v54, v138
	v_mov_b32_e32 v55, v139
	v_mov_b32_e32 v56, v140
	v_mov_b32_e32 v57, v141
	v_mov_b32_e32 v58, v142
	v_mov_b32_e32 v59, v143
	v_mov_b32_e32 v10, v4
	v_mov_b32_e32 v11, v6
	v_pk_mul_f32 v[10:11], v[10:11], v[12:13] op_sel_hi:[1,0]
	v_mov_b32_e32 v6, v5
	v_pk_mul_f32 v[4:5], v[6:7], v[12:13] op_sel_hi:[1,0]
	v_cmp_lt_i32_e32 vcc, s26, v40
	v_lshl_add_u64 v[28:29], v[28:29], 0, s[30:31]
	s_or_b64 s[2:3], vcc, s[2:3]
	v_mov_b32_e32 v38, v48
	v_mov_b32_e32 v39, v50
	v_pk_mul_f32 v[10:11], v[10:11], v[38:39]
	v_mov_b32_e32 v38, v52
	v_mov_b32_e32 v39, v54
	v_pk_add_f32 v[38:39], v[38:39], 1.0 op_sel_hi:[1,0]
	v_mov_b32_e32 v60, v56
	v_mov_b32_e32 v61, v58
	v_mov_b32_e32 v50, v49
	v_mov_b32_e32 v54, v53
	v_pk_fma_f32 v[10:11], v[10:11], v[38:39], v[60:61]
	v_pk_mul_f32 v[4:5], v[4:5], v[50:51]
	v_pk_add_f32 v[6:7], v[54:55], 1.0 op_sel_hi:[1,0]
	v_mov_b32_e32 v58, v57
	v_pk_fma_f32 v[4:5], v[4:5], v[6:7], v[58:59]
	v_cvt_pk_bf16_f32 v4, v10, v4
	v_cvt_pk_bf16_f32 v5, v11, v5
	global_store_dwordx2 v[8:9], v[4:5], off offset:-3072 nt
	v_lshl_add_u64 v[10:11], v[36:37], 0, v[34:35]
	s_waitcnt vmcnt(3)
	v_mov_b32_e32 v4, v144
	v_mov_b32_e32 v5, v145
	v_mov_b32_e32 v6, v146
	v_mov_b32_e32 v7, v147
	v_mov_b32_e32 v36, v148
	v_mov_b32_e32 v37, v149
	v_mov_b32_e32 v38, v150
	v_mov_b32_e32 v39, v151
	v_mov_b32_e32 v48, v152
	v_mov_b32_e32 v49, v153
	v_mov_b32_e32 v50, v154
	v_mov_b32_e32 v51, v155
	v_mov_b32_e32 v10, v0
	v_mov_b32_e32 v11, v2
	v_pk_mul_f32 v[10:11], v[10:11], v[12:13] op_sel_hi:[1,0]
	v_mov_b32_e32 v2, v1
	v_pk_mul_f32 v[0:1], v[2:3], v[12:13] op_sel_hi:[1,0]
	v_mov_b32_e32 v14, v4
	v_mov_b32_e32 v15, v6
	v_pk_mul_f32 v[10:11], v[10:11], v[14:15]
	v_mov_b32_e32 v15, v38
	v_mov_b32_e32 v6, v5
	v_mov_b32_e32 v38, v37
	v_mov_b32_e32 v14, v36
	v_mov_b32_e32 v53, v50
	v_pk_mul_f32 v[0:1], v[0:1], v[6:7]
	v_pk_add_f32 v[2:3], v[38:39], 1.0 op_sel_hi:[1,0]
	v_mov_b32_e32 v50, v49
	v_pk_add_f32 v[14:15], v[14:15], 1.0 op_sel_hi:[1,0]
	v_mov_b32_e32 v52, v48
	v_pk_fma_f32 v[0:1], v[0:1], v[2:3], v[50:51]
	v_pk_fma_f32 v[10:11], v[10:11], v[14:15], v[52:53]
	v_cvt_pk_bf16_f32 v1, v11, v1
	v_cvt_pk_bf16_f32 v0, v10, v0
	global_store_dwordx2 v[8:9], v[0:1], off offset:-2560 nt
	s_andn2_b64 exec, exec, s[2:3]
	s_cbranch_execnz .LBB0_34

.LBB0_182:
	v_min_i32_e32 v2, 0x4000, v16
	v_ashrrev_i32_e32 v2, 13, v2
	v_mov_b32_e32 v53, v193
	v_lshlrev_b64 v[60:61], 11, v[16:17]
	v_add_u32_e32 v2, s8, v2
	v_lshl_add_u64 v[0:1], v[0:1], 0, v[52:53]
	v_lshl_add_u64 v[16:17], v[44:45], 0, v[60:61]
	v_mul_hi_i32_i24_e32 v63, 0x6000, v2
	v_mul_i32_i24_e32 v62, 0x6000, v2
	global_load_dwordx4 v[12:15], v[0:1], off nt
	global_load_dwordx4 v[8:11], v[0:1], off offset:1024 nt
	global_load_dwordx4 v[4:7], v[0:1], off offset:2048 nt
	s_nop 0
	global_load_dwordx4 v[0:3], v[0:1], off offset:3072 nt
	s_nop 0
	global_load_dwordx2 v[24:25], v[16:17], off nt
	global_load_dwordx2 v[32:33], v[16:17], off offset:512 nt
	global_load_dwordx2 v[40:41], v[16:17], off offset:1024 nt
	global_load_dwordx2 v[76:77], v[16:17], off offset:1536 nt
	v_lshl_add_u64 v[18:19], s[90:91], 0, v[62:63]
	v_lshl_add_u64 v[20:21], v[18:19], 0, v[52:53]
	s_mov_b64 s[0:1], 0x345a000
	v_lshl_add_u64 v[84:85], v[20:21], 0, s[0:1]
	s_mov_b32 s0, 0x345a000
	v_add_co_u32_e32 v20, vcc, s0, v20
	global_load_dwordx4 v[16:19], v[46:47], off
	s_nop 0
	v_addc_co_u32_e32 v21, vcc, 0, v21, vcc
	global_load_dwordx4 v[20:23], v[20:21], off
	s_mov_b32 s0, 0x800000
	s_mov_b64 s[10:11], 0x3000
	v_mov_b32_e32 v59, v193
	s_waitcnt vmcnt(5)
	v_and_b32_e32 v67, 0xffff0000, v24
	s_waitcnt vmcnt(4)
	v_and_b32_e32 v69, 0xffff0000, v32
	v_lshlrev_b32_e32 v66, 16, v24
	v_lshlrev_b32_e32 v68, 16, v32
	v_mov_b32_e32 v34, v67
	v_mov_b32_e32 v35, v69
	v_lshlrev_b32_e32 v70, 16, v25
	v_and_b32_e32 v73, 0xffff0000, v33
	v_lshlrev_b32_e32 v72, 16, v33
	v_mov_b32_e32 v32, v66
	v_mov_b32_e32 v33, v68
	v_pk_mul_f32 v[34:35], v[34:35], v[34:35]
	v_and_b32_e32 v71, 0xffff0000, v25
	global_load_dwordx4 v[28:31], v[46:47], off offset:1024
	global_load_dwordx4 v[24:27], v[84:85], off offset:1024
	v_pk_fma_f32 v[32:33], v[32:33], v[32:33], v[34:35]
	v_mov_b32_e32 v34, v70
	v_mov_b32_e32 v35, v72
	v_mov_b32_e32 v36, v71
	v_mov_b32_e32 v37, v73
	v_pk_fma_f32 v[32:33], v[34:35], v[34:35], v[32:33]
	s_waitcnt vmcnt(5)
	v_and_b32_e32 v75, 0xffff0000, v40
	v_pk_fma_f32 v[78:79], v[36:37], v[36:37], v[32:33]
	global_load_dwordx4 v[36:39], v[46:47], off offset:2048
	global_load_dwordx4 v[32:35], v[84:85], off offset:2048
	v_lshlrev_b32_e32 v74, 16, v40
	v_and_b32_e32 v83, 0xffff0000, v41
	v_lshlrev_b32_e32 v82, 16, v41
	global_load_dwordx4 v[40:43], v[46:47], off offset:3072
	global_load_dwordx4 v[92:95], v[84:85], off offset:3072
	s_waitcnt vmcnt(8)
	v_and_b32_e32 v81, 0xffff0000, v76
	v_lshlrev_b32_e32 v80, 16, v76
	v_mov_b32_e32 v96, v75
	v_mov_b32_e32 v97, v81
	v_and_b32_e32 v85, 0xffff0000, v77
	v_lshlrev_b32_e32 v84, 16, v77
	v_mov_b32_e32 v76, v74
	v_mov_b32_e32 v77, v80
	v_pk_mul_f32 v[96:97], v[96:97], v[96:97]
	v_mov_b32_e32 v98, v83
	v_pk_fma_f32 v[76:77], v[76:77], v[76:77], v[96:97]
	v_mov_b32_e32 v96, v82
	v_mov_b32_e32 v97, v84
	v_mov_b32_e32 v99, v85
	v_pk_fma_f32 v[76:77], v[96:97], v[96:97], v[76:77]
	v_add_f32_e32 v55, v78, v79
	v_pk_fma_f32 v[76:77], v[98:99], v[98:99], v[76:77]
	s_nop 0
	v_add_f32_e32 v55, v55, v76
	v_add_f32_e32 v55, v55, v77
	ds_bpermute_b32 v57, v86, v55
	s_waitcnt lgkmcnt(0)
	v_add_f32_e32 v55, v55, v57
	ds_bpermute_b32 v57, v87, v55
	s_waitcnt lgkmcnt(0)
	v_add_f32_e32 v55, v55, v57
	ds_bpermute_b32 v57, v88, v55
	s_waitcnt lgkmcnt(0)
	v_add_f32_e32 v55, v55, v57
	ds_bpermute_b32 v57, v89, v55
	s_waitcnt lgkmcnt(0)
	v_add_f32_e32 v55, v55, v57
	ds_bpermute_b32 v57, v90, v55
	s_waitcnt lgkmcnt(0)
	v_add_f32_e32 v55, v55, v57
	ds_bpermute_b32 v57, v91, v55
	s_waitcnt lgkmcnt(0)
	v_add_f32_e32 v55, v55, v57
	v_fmamk_f32 v55, v55, 0x3a800000, v219
	v_cmp_gt_f32_e32 vcc, s0, v55
	v_mul_f32_e32 v57, 0x4b800000, v55
	s_nop 0
	v_cndmask_b32_e32 v55, v55, v57, vcc
	v_rsq_f32_e32 v55, v55
	s_nop 0
	v_mul_f32_e32 v57, 0x45800000, v55
	v_cndmask_b32_e32 v76, v55, v57, vcc
	v_pk_mul_f32 v[66:67], v[76:77], v[66:67] op_sel_hi:[0,1]
	s_waitcnt vmcnt(7)
	v_pk_mul_f32 v[16:17], v[16:17], v[66:67]
	v_pk_mul_f32 v[66:67], v[76:77], v[70:71] op_sel_hi:[0,1]
	s_waitcnt vmcnt(6)
	v_pk_fma_f32 v[12:13], v[20:21], v[16:17], v[12:13]
	v_pk_mul_f32 v[16:17], v[76:77], v[68:69] op_sel_hi:[0,1]
	v_pk_mul_f32 v[18:19], v[18:19], v[66:67]
	s_waitcnt vmcnt(5)
	v_pk_mul_f32 v[16:17], v[28:29], v[16:17]
	v_pk_fma_f32 v[14:15], v[22:23], v[18:19], v[14:15]
	v_pk_mul_f32 v[18:19], v[76:77], v[72:73] op_sel_hi:[0,1]
	s_waitcnt vmcnt(4)
	v_pk_fma_f32 v[8:9], v[24:25], v[16:17], v[8:9]
	v_pk_mul_f32 v[16:17], v[76:77], v[74:75] op_sel_hi:[0,1]
	v_pk_mul_f32 v[18:19], v[30:31], v[18:19]
	s_waitcnt vmcnt(3)
	v_pk_mul_f32 v[16:17], v[16:17], v[36:37]
	v_pk_fma_f32 v[10:11], v[26:27], v[18:19], v[10:11]
	v_pk_mul_f32 v[18:19], v[76:77], v[82:83] op_sel_hi:[0,1]
	s_waitcnt vmcnt(2)
	v_pk_fma_f32 v[4:5], v[16:17], v[32:33], v[4:5]
	v_pk_mul_f32 v[16:17], v[76:77], v[80:81] op_sel_hi:[0,1]
	v_mov_b32_e32 v22, v13
	v_mov_b32_e32 v23, v9
	v_pk_mul_f32 v[18:19], v[18:19], v[38:39]
	s_waitcnt vmcnt(1)
	v_pk_mul_f32 v[16:17], v[16:17], v[40:41]
	v_mov_b32_e32 v20, v12
	v_mov_b32_e32 v21, v8
	v_pk_mul_f32 v[22:23], v[22:23], v[22:23]
	v_pk_fma_f32 v[6:7], v[18:19], v[34:35], v[6:7]
	v_pk_mul_f32 v[18:19], v[76:77], v[84:85] op_sel_hi:[0,1]
	s_waitcnt vmcnt(0)
	v_pk_fma_f32 v[0:1], v[16:17], v[92:93], v[0:1]
	v_pk_fma_f32 v[20:21], v[20:21], v[20:21], v[22:23]
	v_mov_b32_e32 v22, v14
	v_mov_b32_e32 v23, v10
	v_pk_mul_f32 v[18:19], v[18:19], v[42:43]
	v_pk_fma_f32 v[20:21], v[22:23], v[22:23], v[20:21]
	v_mov_b32_e32 v22, v15
	v_mov_b32_e32 v23, v11
	v_mov_b32_e32 v24, v5
	v_mov_b32_e32 v25, v1
	v_pk_fma_f32 v[2:3], v[18:19], v[94:95], v[2:3]
	v_pk_fma_f32 v[20:21], v[22:23], v[22:23], v[20:21]
	v_mov_b32_e32 v22, v4
	v_mov_b32_e32 v23, v0
	v_pk_mul_f32 v[24:25], v[24:25], v[24:25]
	v_lshl_add_u64 v[16:17], v[64:65], 0, v[52:53]
	v_pk_fma_f32 v[22:23], v[22:23], v[22:23], v[24:25]
	v_mov_b32_e32 v24, v6
	v_mov_b32_e32 v25, v2
	v_pk_fma_f32 v[22:23], v[24:25], v[24:25], v[22:23]
	v_mov_b32_e32 v24, v7
	v_mov_b32_e32 v25, v3
	v_pk_fma_f32 v[22:23], v[24:25], v[24:25], v[22:23]
	v_add_f32_e32 v20, v20, v21
	global_store_dwordx4 v[16:17], v[12:15], off nt
	global_store_dwordx4 v[16:17], v[8:11], off offset:1024 nt
	global_store_dwordx4 v[16:17], v[4:7], off offset:2048 nt
	global_store_dwordx4 v[16:17], v[0:3], off offset:3072 nt
	v_lshl_add_u64 v[16:17], s[96:97], 0, v[62:63]
	v_add_f32_e32 v20, v20, v22
	v_lshl_add_u64 v[18:19], v[16:17], 0, s[10:11]
	v_add_f32_e32 v22, v20, v23
	s_mov_b64 s[10:11], 0x4000
	v_lshl_add_u64 v[20:21], v[16:17], 0, s[10:11]
	ds_bpermute_b32 v16, v86, v22
	v_lshl_add_u64 v[26:27], v[20:21], 0, v[52:53]
	v_lshl_add_u64 v[30:31], v[18:19], 0, v[52:53]
	v_mov_b32_e32 v34, v12
	v_mov_b32_e32 v35, v14
	s_waitcnt lgkmcnt(0)
	v_add_f32_e32 v16, v22, v16
	global_load_dwordx4 v[22:25], v[48:49], off
	s_nop 0
	global_load_dwordx4 v[26:29], v[26:27], off
	s_nop 0
	global_load_dwordx4 v[30:33], v[30:31], off
	global_load_dwordx4 v[106:109], v[48:49], off offset:1024
	v_mov_b32_e32 v100, v54
	v_mov_b32_e32 v101, v193
	v_lshl_add_u64 v[100:101], v[20:21], 0, v[100:101]
	global_load_dwordx4 v[116:119], v[100:101], off
	v_mov_b32_e32 v100, v54
	v_mov_b32_e32 v101, v193
	v_lshl_add_u64 v[100:101], v[18:19], 0, v[100:101]
	global_load_dwordx4 v[120:123], v[100:101], off
	global_load_dwordx4 v[124:127], v[48:49], off offset:2048
	v_mov_b32_e32 v100, v56
	v_mov_b32_e32 v101, v193
	v_lshl_add_u64 v[100:101], v[20:21], 0, v[100:101]
	global_load_dwordx4 v[136:139], v[100:101], off
	v_mov_b32_e32 v100, v56
	v_mov_b32_e32 v101, v193
	v_lshl_add_u64 v[100:101], v[18:19], 0, v[100:101]
	global_load_dwordx4 v[140:143], v[100:101], off
	global_load_dwordx4 v[144:147], v[48:49], off offset:3072
	v_mov_b32_e32 v100, v58
	v_mov_b32_e32 v101, v193
	v_lshl_add_u64 v[100:101], v[20:21], 0, v[100:101]
	global_load_dwordx4 v[148:151], v[100:101], off
	v_mov_b32_e32 v100, v58
	v_mov_b32_e32 v101, v193
	v_lshl_add_u64 v[100:101], v[18:19], 0, v[100:101]
	global_load_dwordx4 v[152:155], v[100:101], off
	ds_bpermute_b32 v17, v87, v16
	v_mov_b32_e32 v14, v13
	v_mov_b32_e32 v55, v193
	v_mov_b32_e32 v57, v193
	s_waitcnt lgkmcnt(0)
	v_add_f32_e32 v16, v16, v17
	ds_bpermute_b32 v17, v88, v16
	s_waitcnt lgkmcnt(0)
	v_add_f32_e32 v16, v16, v17
	ds_bpermute_b32 v17, v89, v16
	s_waitcnt lgkmcnt(0)
	v_add_f32_e32 v16, v16, v17
	ds_bpermute_b32 v17, v90, v16
	s_waitcnt lgkmcnt(0)
	v_add_f32_e32 v16, v16, v17
	ds_bpermute_b32 v17, v91, v16
	s_waitcnt lgkmcnt(0)
	v_add_f32_e32 v16, v16, v17
	v_fmamk_f32 v16, v16, 0x3a800000, v219
	v_cmp_gt_f32_e32 vcc, s0, v16
	v_mul_f32_e32 v17, 0x4b800000, v16
	v_readlane_b32 s0, v255, 11
	v_cndmask_b32_e32 v16, v16, v17, vcc
	v_rsq_f32_e32 v16, v16
	v_add_u32_e32 v192, s0, v192
	s_movk_i32 s0, 0x1ff
	v_readlane_b32 s1, v255, 12
	v_mul_f32_e32 v17, 0x45800000, v16
	v_cndmask_b32_e32 v16, v16, v17, vcc
	v_pk_mul_f32 v[34:35], v[34:35], v[16:17] op_sel_hi:[1,0]
	v_pk_mul_f32 v[12:13], v[14:15], v[16:17] op_sel_hi:[1,0]
	v_cmp_lt_i32_e32 vcc, s0, v192
	s_or_b64 s[6:7], vcc, s[6:7]
	s_waitcnt vmcnt(11)
	v_mov_b32_e32 v36, v22
	v_mov_b32_e32 v37, v24
	v_pk_mul_f32 v[34:35], v[36:37], v[34:35]
	s_waitcnt vmcnt(10)
	v_mov_b32_e32 v36, v26
	v_mov_b32_e32 v37, v28
	v_pk_add_f32 v[36:37], v[36:37], 1.0 op_sel_hi:[1,0]
	s_waitcnt vmcnt(9)
	v_mov_b32_e32 v38, v30
	v_mov_b32_e32 v39, v32
	v_mov_b32_e32 v24, v23
	v_mov_b32_e32 v28, v27
	v_pk_fma_f32 v[34:35], v[36:37], v[34:35], v[38:39]
	v_pk_mul_f32 v[12:13], v[24:25], v[12:13]
	v_pk_add_f32 v[14:15], v[28:29], 1.0 op_sel_hi:[1,0]
	v_mov_b32_e32 v32, v31
	v_pk_fma_f32 v[12:13], v[14:15], v[12:13], v[32:33]
	v_and_b32_sdwa v15, v34, v218 dst_sel:DWORD dst_unused:UNUSED_PAD src0_sel:WORD_1 src1_sel:DWORD
	v_add3_u32 v17, v34, v15, s80
	v_and_b32_sdwa v22, v12, v218 dst_sel:DWORD dst_unused:UNUSED_PAD src0_sel:WORD_1 src1_sel:DWORD
	v_cvt_pk_bf16_f32 v15, v35, v13
	v_add3_u32 v12, v12, v22, s80
	v_and_b32_e32 v12, 0xffff0000, v12
	v_or_b32_sdwa v14, v12, v17 dst_sel:DWORD dst_unused:UNUSED_PAD src0_sel:DWORD src1_sel:WORD_1
	v_lshl_add_u64 v[12:13], v[50:51], 0, v[60:61]
	global_store_dwordx2 v[12:13], v[14:15], off nt
	v_lshl_add_u64 v[30:31], v[18:19], 0, v[54:55]
	v_lshl_add_u64 v[14:15], v[20:21], 0, v[54:55]
	s_waitcnt vmcnt(7)
	v_mov_b32_e32 v22, v106
	v_mov_b32_e32 v23, v107
	v_mov_b32_e32 v24, v108
	v_mov_b32_e32 v25, v109
	v_mov_b32_e32 v26, v116
	v_mov_b32_e32 v27, v117
	v_mov_b32_e32 v28, v118
	v_mov_b32_e32 v29, v119
	s_nop 0
	v_mov_b32_e32 v30, v120
	v_mov_b32_e32 v31, v121
	v_mov_b32_e32 v32, v122
	v_mov_b32_e32 v33, v123
	v_mov_b32_e32 v14, v8
	v_mov_b32_e32 v15, v10
	v_pk_mul_f32 v[14:15], v[14:15], v[16:17] op_sel_hi:[1,0]
	v_mov_b32_e32 v10, v9
	v_pk_mul_f32 v[8:9], v[10:11], v[16:17] op_sel_hi:[1,0]
	v_mov_b32_e32 v34, v22
	v_mov_b32_e32 v35, v24
	v_pk_mul_f32 v[14:15], v[14:15], v[34:35]
	v_mov_b32_e32 v34, v26
	v_mov_b32_e32 v35, v28
	v_pk_add_f32 v[34:35], v[34:35], 1.0 op_sel_hi:[1,0]
	v_mov_b32_e32 v36, v30
	v_mov_b32_e32 v37, v32
	v_mov_b32_e32 v24, v23
	v_mov_b32_e32 v28, v27
	v_pk_fma_f32 v[14:15], v[14:15], v[34:35], v[36:37]
	v_pk_mul_f32 v[8:9], v[8:9], v[24:25]
	v_pk_add_f32 v[10:11], v[28:29], 1.0 op_sel_hi:[1,0]
	v_mov_b32_e32 v32, v31
	v_pk_fma_f32 v[8:9], v[8:9], v[10:11], v[32:33]
	v_cvt_pk_bf16_f32 v8, v14, v8
	v_cvt_pk_bf16_f32 v9, v15, v9
	global_store_dwordx2 v[12:13], v[8:9], off offset:512 nt
	v_lshl_add_u64 v[26:27], v[18:19], 0, v[56:57]
	v_lshl_add_u64 v[14:15], v[20:21], 0, v[56:57]
	s_waitcnt vmcnt(5)
	v_mov_b32_e32 v8, v124
	v_mov_b32_e32 v9, v125
	v_mov_b32_e32 v10, v126
	v_mov_b32_e32 v11, v127
	v_mov_b32_e32 v22, v136
	v_mov_b32_e32 v23, v137
	v_mov_b32_e32 v24, v138
	v_mov_b32_e32 v25, v139
	s_nop 0
	v_mov_b32_e32 v26, v140
	v_mov_b32_e32 v27, v141
	v_mov_b32_e32 v28, v142
	v_mov_b32_e32 v29, v143
	v_mov_b32_e32 v14, v4
	v_mov_b32_e32 v15, v6
	v_pk_mul_f32 v[14:15], v[14:15], v[16:17] op_sel_hi:[1,0]
	v_mov_b32_e32 v6, v5
	v_pk_mul_f32 v[4:5], v[6:7], v[16:17] op_sel_hi:[1,0]
	v_mov_b32_e32 v30, v8
	v_mov_b32_e32 v31, v10
	v_pk_mul_f32 v[14:15], v[14:15], v[30:31]
	v_mov_b32_e32 v31, v24
	v_mov_b32_e32 v10, v9
	v_mov_b32_e32 v24, v23
	v_mov_b32_e32 v30, v22
	v_mov_b32_e32 v33, v28
	v_pk_mul_f32 v[4:5], v[4:5], v[10:11]
	v_pk_add_f32 v[6:7], v[24:25], 1.0 op_sel_hi:[1,0]
	v_mov_b32_e32 v28, v27
	v_pk_add_f32 v[30:31], v[30:31], 1.0 op_sel_hi:[1,0]
	v_mov_b32_e32 v32, v26
	v_pk_fma_f32 v[4:5], v[4:5], v[6:7], v[28:29]
	v_pk_fma_f32 v[14:15], v[14:15], v[30:31], v[32:33]
	v_cvt_pk_bf16_f32 v5, v15, v5
	v_cvt_pk_bf16_f32 v4, v14, v4
	global_store_dwordx2 v[12:13], v[4:5], off offset:1024 nt
	v_lshl_add_u64 v[8:9], v[20:21], 0, v[58:59]
	v_lshl_add_u64 v[14:15], v[18:19], 0, v[58:59]
	s_waitcnt vmcnt(3)
	v_mov_b32_e32 v4, v144
	v_mov_b32_e32 v5, v145
	v_mov_b32_e32 v6, v146
	v_mov_b32_e32 v7, v147
	s_nop 0
	v_mov_b32_e32 v8, v148
	v_mov_b32_e32 v9, v149
	v_mov_b32_e32 v10, v150
	v_mov_b32_e32 v11, v151
	s_nop 0
	v_mov_b32_e32 v18, v152
	v_mov_b32_e32 v19, v153
	v_mov_b32_e32 v20, v154
	v_mov_b32_e32 v21, v155
	v_mov_b32_e32 v14, v0
	v_mov_b32_e32 v15, v2
	v_pk_mul_f32 v[14:15], v[14:15], v[16:17] op_sel_hi:[1,0]
	v_mov_b32_e32 v2, v1
	v_pk_mul_f32 v[0:1], v[2:3], v[16:17] op_sel_hi:[1,0]
	v_mov_b32_e32 v22, v4
	v_mov_b32_e32 v23, v6
	v_pk_mul_f32 v[14:15], v[14:15], v[22:23]
	v_mov_b32_e32 v23, v10
	v_mov_b32_e32 v6, v5
	v_mov_b32_e32 v10, v9
	v_mov_b32_e32 v22, v8
	v_mov_b32_e32 v25, v20
	v_pk_mul_f32 v[0:1], v[0:1], v[6:7]
	v_pk_add_f32 v[2:3], v[10:11], 1.0 op_sel_hi:[1,0]
	v_mov_b32_e32 v20, v19
	v_pk_add_f32 v[22:23], v[22:23], 1.0 op_sel_hi:[1,0]
	v_mov_b32_e32 v24, v18
	v_pk_fma_f32 v[0:1], v[0:1], v[2:3], v[20:21]
	v_pk_fma_f32 v[14:15], v[14:15], v[22:23], v[24:25]
	v_cvt_pk_bf16_f32 v1, v15, v1
	v_cvt_pk_bf16_f32 v0, v14, v0
	global_store_dwordx2 v[12:13], v[0:1], off offset:1536 nt
	s_andn2_b64 exec, exec, s[6:7]
	s_cbranch_execz .LBB0_188

.LBB0_1030:
	s_or_b64 exec, exec, s[4:5]
	v_lshl_add_u64 v[0:1], v[0:1], 0, v[192:193]
	global_load_dwordx4 v[36:39], v[0:1], off nt
	global_load_dwordx4 v[8:11], v[0:1], off offset:1024 nt
	global_load_dwordx4 v[4:7], v[0:1], off offset:2048 nt
	s_nop 0
	global_load_dwordx4 v[0:3], v[0:1], off offset:3072 nt
	s_nop 0
	global_load_dwordx4 v[40:43], v[14:15], off
	v_min_i32_e32 v13, 0x4000, v28
	v_ashrrev_i32_e32 v13, 13, v13
	v_mul_hi_i32_i24_e32 v25, 0x6000, v13
	v_mul_i32_i24_e32 v24, 0x6000, v13
	v_lshl_add_u64 v[26:27], s[96:97], 0, v[24:25]
	s_mov_b64 s[4:5], 0x1000
	v_lshl_add_u64 v[24:25], v[26:27], 0, v[192:193]
	v_lshl_add_u64 v[26:27], v[26:27], 0, s[4:5]
	v_lshl_add_u64 v[48:49], v[26:27], 0, v[192:193]
	global_load_dwordx4 v[44:47], v[24:25], off
	s_mov_b32 s4, 0x800000
	global_load_dwordx4 v[48:51], v[48:49], off
	global_load_dwordx4 v[68:71], v[14:15], off offset:1024
	v_mov_b32_e32 v88, v18
	v_mov_b32_e32 v89, v193
	v_lshl_add_u64 v[88:89], v[26:27], 0, v[88:89]
	global_load_dwordx4 v[72:75], v[88:89], off
	global_load_dwordx4 v[76:79], v[24:25], off offset:1024
	global_load_dwordx4 v[84:87], v[14:15], off offset:2048
	v_mov_b32_e32 v88, v20
	v_mov_b32_e32 v89, v193
	v_lshl_add_u64 v[88:89], v[26:27], 0, v[88:89]
	global_load_dwordx4 v[92:95], v[88:89], off
	global_load_dwordx4 v[96:99], v[24:25], off offset:2048
	global_load_dwordx4 v[106:109], v[14:15], off offset:3072
	v_mov_b32_e32 v88, v22
	v_mov_b32_e32 v89, v193
	v_lshl_add_u64 v[88:89], v[26:27], 0, v[88:89]
	global_load_dwordx4 v[116:119], v[88:89], off
	global_load_dwordx4 v[120:123], v[24:25], off offset:3072
	v_lshlrev_b64 v[28:29], 11, v[28:29]
	v_lshl_add_u64 v[28:29], v[16:17], 0, v[28:29]
	s_waitcnt vmcnt(15)
	v_mov_b32_e32 v54, v37
	s_waitcnt vmcnt(14)
	v_mov_b32_e32 v55, v9
	v_mov_b32_e32 v52, v36
	v_mov_b32_e32 v53, v8
	s_waitcnt vmcnt(13)
	v_mov_b32_e32 v62, v5
	s_waitcnt vmcnt(12)
	v_mov_b32_e32 v63, v1
	v_pk_mul_f32 v[54:55], v[54:55], v[54:55]
	v_mov_b32_e32 v56, v38
	v_mov_b32_e32 v57, v10
	v_mov_b32_e32 v60, v4
	v_mov_b32_e32 v61, v0
	v_pk_mul_f32 v[62:63], v[62:63], v[62:63]
	v_pk_fma_f32 v[52:53], v[52:53], v[52:53], v[54:55]
	v_mov_b32_e32 v58, v39
	v_mov_b32_e32 v59, v11
	v_mov_b32_e32 v64, v6
	v_mov_b32_e32 v65, v2
	v_pk_fma_f32 v[54:55], v[60:61], v[60:61], v[62:63]
	v_pk_fma_f32 v[52:53], v[56:57], v[56:57], v[52:53]
	v_mov_b32_e32 v66, v7
	v_mov_b32_e32 v67, v3
	v_pk_fma_f32 v[54:55], v[64:65], v[64:65], v[54:55]
	v_pk_fma_f32 v[52:53], v[58:59], v[58:59], v[52:53]
	v_pk_fma_f32 v[54:55], v[66:67], v[66:67], v[54:55]
	v_add_f32_e32 v13, v52, v53
	v_add_f32_e32 v13, v13, v54
	v_add_f32_e32 v13, v13, v55
	ds_bpermute_b32 v19, v30, v13
	s_waitcnt vmcnt(11)
	v_mov_b32_e32 v53, v42
	v_mov_b32_e32 v42, v41
	v_mov_b32_e32 v41, v38
	v_mov_b32_e32 v38, v37
	s_waitcnt lgkmcnt(0)
	v_add_f32_e32 v13, v13, v19
	ds_bpermute_b32 v19, v31, v13
	s_waitcnt vmcnt(10)
	v_mov_b32_e32 v37, v46
	v_mov_b32_e32 v46, v45
	s_waitcnt vmcnt(9)
	v_mov_b32_e32 v45, v50
	v_mov_b32_e32 v50, v49
	s_waitcnt lgkmcnt(0)
	v_add_f32_e32 v13, v13, v19
	ds_bpermute_b32 v21, v32, v13
	v_mov_b32_e32 v52, v40
	v_mov_b32_e32 v40, v36
	v_mov_b32_e32 v36, v44
	v_mov_b32_e32 v44, v48
	s_waitcnt lgkmcnt(0)
	v_add_f32_e32 v13, v13, v21
	ds_bpermute_b32 v21, v33, v13
	v_pk_add_f32 v[48:49], v[50:51], 1.0 op_sel_hi:[1,0]
	v_pk_add_f32 v[44:45], v[44:45], 1.0 op_sel_hi:[1,0]
	v_mov_b32_e32 v19, v193
	s_waitcnt lgkmcnt(0)
	v_add_f32_e32 v13, v13, v21
	ds_bpermute_b32 v21, v34, v13
	s_waitcnt lgkmcnt(0)
	v_add_f32_e32 v13, v13, v21
	ds_bpermute_b32 v21, v35, v13
	s_waitcnt lgkmcnt(0)
	v_add_f32_e32 v13, v13, v21
	v_fmamk_f32 v13, v13, 0x3a800000, v219
	v_mul_f32_e32 v21, 0x4b800000, v13
	v_cmp_gt_f32_e32 vcc, s4, v13
	v_readlane_b32 s4, v255, 11
	v_readlane_b32 s5, v255, 12
	v_cndmask_b32_e32 v13, v13, v21, vcc
	v_rsq_f32_e32 v13, v13
	v_add_u32_e32 v12, s4, v12
	s_movk_i32 s4, 0x1ff
	v_mul_f32_e32 v21, 0x45800000, v13
	v_cndmask_b32_e32 v50, v13, v21, vcc
	v_pk_mul_f32 v[40:41], v[40:41], v[50:51] op_sel_hi:[1,0]
	v_pk_mul_f32 v[38:39], v[38:39], v[50:51] op_sel_hi:[1,0]
	v_pk_mul_f32 v[40:41], v[52:53], v[40:41]
	v_pk_mul_f32 v[38:39], v[42:43], v[38:39]
	v_pk_fma_f32 v[36:37], v[44:45], v[40:41], v[36:37]
	v_pk_fma_f32 v[38:39], v[48:49], v[38:39], v[46:47]
	v_cvt_pk_bf16_f32 v36, v36, v38
	v_cvt_pk_bf16_f32 v37, v37, v39
	global_store_dwordx2 v[28:29], v[36:37], off nt
	s_waitcnt vmcnt(7)
	v_mov_b32_e32 v36, v68
	v_mov_b32_e32 v37, v69
	v_mov_b32_e32 v38, v70
	v_mov_b32_e32 v39, v71
	v_lshl_add_u64 v[40:41], v[26:27], 0, v[18:19]
	v_mov_b32_e32 v40, v72
	v_mov_b32_e32 v41, v73
	v_mov_b32_e32 v42, v74
	v_mov_b32_e32 v43, v75
	s_nop 0
	v_mov_b32_e32 v44, v76
	v_mov_b32_e32 v45, v77
	v_mov_b32_e32 v46, v78
	v_mov_b32_e32 v47, v79
	v_mov_b32_e32 v48, v8
	v_mov_b32_e32 v49, v10
	v_mov_b32_e32 v10, v9
	v_pk_mul_f32 v[8:9], v[48:49], v[50:51] op_sel_hi:[1,0]
	v_pk_mul_f32 v[10:11], v[10:11], v[50:51] op_sel_hi:[1,0]
	v_mov_b32_e32 v21, v193
	v_cmp_lt_i32_e32 vcc, s4, v12
	s_or_b64 s[2:3], vcc, s[2:3]
	v_mov_b32_e32 v49, v38
	v_mov_b32_e32 v53, v42
	v_mov_b32_e32 v38, v37
	v_mov_b32_e32 v42, v41
	v_mov_b32_e32 v48, v36
	v_mov_b32_e32 v52, v40
	v_mov_b32_e32 v55, v46
	v_mov_b32_e32 v46, v45
	v_pk_mul_f32 v[10:11], v[10:11], v[38:39]
	v_pk_add_f32 v[38:39], v[42:43], 1.0 op_sel_hi:[1,0]
	v_mov_b32_e32 v54, v44
	v_pk_mul_f32 v[8:9], v[8:9], v[48:49]
	v_pk_add_f32 v[36:37], v[52:53], 1.0 op_sel_hi:[1,0]
	v_pk_fma_f32 v[10:11], v[10:11], v[38:39], v[46:47]
	v_pk_fma_f32 v[8:9], v[8:9], v[36:37], v[54:55]
	v_cvt_pk_bf16_f32 v9, v9, v11
	v_cvt_pk_bf16_f32 v8, v8, v10
	global_store_dwordx2 v[28:29], v[8:9], off offset:512 nt
	s_waitcnt vmcnt(5)
	v_mov_b32_e32 v8, v84
	v_mov_b32_e32 v9, v85
	v_mov_b32_e32 v10, v86
	v_mov_b32_e32 v11, v87
	v_lshl_add_u64 v[36:37], v[26:27], 0, v[20:21]
	v_mov_b32_e32 v36, v92
	v_mov_b32_e32 v37, v93
	v_mov_b32_e32 v38, v94
	v_mov_b32_e32 v39, v95
	s_nop 0
	v_mov_b32_e32 v40, v96
	v_mov_b32_e32 v41, v97
	v_mov_b32_e32 v42, v98
	v_mov_b32_e32 v43, v99
	v_mov_b32_e32 v44, v4
	v_mov_b32_e32 v45, v6
	v_mov_b32_e32 v6, v5
	v_pk_mul_f32 v[4:5], v[44:45], v[50:51] op_sel_hi:[1,0]
	v_pk_mul_f32 v[6:7], v[6:7], v[50:51] op_sel_hi:[1,0]
	v_mov_b32_e32 v23, v193
	v_mov_b32_e32 v45, v10
	v_mov_b32_e32 v47, v38
	v_mov_b32_e32 v10, v9
	v_mov_b32_e32 v38, v37
	v_mov_b32_e32 v44, v8
	v_mov_b32_e32 v46, v36
	v_mov_b32_e32 v49, v42
	v_mov_b32_e32 v42, v41
	v_pk_mul_f32 v[6:7], v[6:7], v[10:11]
	v_pk_add_f32 v[10:11], v[38:39], 1.0 op_sel_hi:[1,0]
	v_mov_b32_e32 v48, v40
	v_pk_mul_f32 v[4:5], v[4:5], v[44:45]
	v_pk_add_f32 v[8:9], v[46:47], 1.0 op_sel_hi:[1,0]
	v_pk_fma_f32 v[6:7], v[6:7], v[10:11], v[42:43]
	v_pk_fma_f32 v[4:5], v[4:5], v[8:9], v[48:49]
	v_cvt_pk_bf16_f32 v5, v5, v7
	v_cvt_pk_bf16_f32 v4, v4, v6
	global_store_dwordx2 v[28:29], v[4:5], off offset:1024 nt
	s_waitcnt vmcnt(3)
	v_mov_b32_e32 v4, v106
	v_mov_b32_e32 v5, v107
	v_mov_b32_e32 v6, v108
	v_mov_b32_e32 v7, v109
	v_lshl_add_u64 v[8:9], v[26:27], 0, v[22:23]
	v_mov_b32_e32 v8, v116
	v_mov_b32_e32 v9, v117
	v_mov_b32_e32 v10, v118
	v_mov_b32_e32 v11, v119
	s_nop 0
	v_mov_b32_e32 v24, v120
	v_mov_b32_e32 v25, v121
	v_mov_b32_e32 v26, v122
	v_mov_b32_e32 v27, v123
	v_mov_b32_e32 v36, v0
	v_mov_b32_e32 v37, v2
	v_mov_b32_e32 v2, v1
	v_pk_mul_f32 v[0:1], v[36:37], v[50:51] op_sel_hi:[1,0]
	v_pk_mul_f32 v[2:3], v[2:3], v[50:51] op_sel_hi:[1,0]
	v_mov_b32_e32 v37, v6
	v_mov_b32_e32 v39, v10
	v_mov_b32_e32 v6, v5
	v_mov_b32_e32 v10, v9
	v_mov_b32_e32 v36, v4
	v_mov_b32_e32 v38, v8
	v_mov_b32_e32 v41, v26
	v_mov_b32_e32 v26, v25
	v_pk_mul_f32 v[2:3], v[2:3], v[6:7]
	v_pk_add_f32 v[6:7], v[10:11], 1.0 op_sel_hi:[1,0]
	v_mov_b32_e32 v40, v24
	v_pk_mul_f32 v[0:1], v[0:1], v[36:37]
	v_pk_add_f32 v[4:5], v[38:39], 1.0 op_sel_hi:[1,0]
	v_pk_fma_f32 v[2:3], v[2:3], v[6:7], v[26:27]
	v_pk_fma_f32 v[0:1], v[0:1], v[4:5], v[40:41]
	v_cvt_pk_bf16_f32 v1, v1, v3
	v_cvt_pk_bf16_f32 v0, v0, v2
	global_store_dwordx2 v[28:29], v[0:1], off offset:1536 nt
	s_andn2_b64 exec, exec, s[2:3]
	s_cbranch_execz .LBB0_1035
